# leader fast-exit: XCD leaders no longer issue (and wait on) the unobserved XGEN release atomic, on top of TOP polling, early invalidate and the 75 percent early write-back
# speedup vs baseline: 1.0113x; 1.0079x over previous
; __device__ __forceinline__ unsigned xb_ld(unsigned* p)              { return __hip_atomic_load(p, __ATOMIC_RELAXED, __HIP_MEMORY_SCOPE_AGENT); }
; __device__ __forceinline__ unsigned xb_add(unsigned* p, unsigned v) { return __hip_atomic_fetch_add(p, v, __ATOMIC_RELAXED, __HIP_MEMORY_SCOPE_AGENT); }
; #define XB_SPIN(cond, bar) do { unsigned _sp = 0; while (cond) { __builtin_amdgcn_s_sleep(0); \
;     if ((++_sp & 255u) == 0u) { if (xb_ld(&(bar)[XB_TMO])) break; if (_sp > XB_SPIN_CAP) { atomicAdd(&(bar)[XB_TMO], 1u); break; } } } } while (0)
; __device__ __forceinline__ void xcd_barrier(const XcdBarrier& b) {
;     ...
;             const unsigned og = xb_add(&bar[XB_TOP], 1u);
;             const unsigned tg = og / nx;
;             if (og + 1u == (tg + 1u) * nx) xb_add(&bar[XB_TOPGEN], 1u);
;             else XB_SPIN(xb_ld(&bar[XB_TOPGEN]) == tg, bar);
;             __builtin_amdgcn_fence(__ATOMIC_ACQUIRE, "agent");
;             xb_add(&bar[XB_XGEN(b.x)], 1u);
;             asm volatile("s_waitcnt vmcnt(0)" ::: "memory");
.LBB0_186:
	s_or_b64 exec, exec, s[0:1]
	s_mov_b64 s[0:1], exec
	v_mbcnt_lo_u32_b32 v0, s0, 0
	v_mbcnt_hi_u32_b32 v0, s1, v0
	v_cmp_eq_u32_e32 vcc, 0, v0
	s_waitcnt vmcnt(0)
	s_and_saveexec_b64 s[2:3], vcc
	s_cbranch_execz .LBB0_188
	s_bcnt1_i32_b64 s0, s[0:1]
	v_mov_b32_e32 v0, s0
	v_readlane_b32 s0, v252, 5
	v_readlane_b32 s1, v252, 6
	s_nop 4
	s_nop 0
